# panel-ready handoff: invalidate issued before the poll loop and the poll loop runs without its s_sleep
# speedup vs baseline: 1.0038x; 1.0038x over previous
.LBB0_207:
	s_memrealtime s[16:17]
	s_waitcnt lgkmcnt(0)
	s_sub_u32 s16, s16, s8
	s_subb_u32 s17, s17, s9
	v_cmp_lt_u64_e32 vcc, s[16:17], v[2:3]
	s_cbranch_vccz .LBB0_199
	s_add_i32 s11, s11, 1
	s_mov_b64 s[18:19], 0
	s_nop 0
	s_branch .LBB0_199

.LBB0_236:
	s_memrealtime s[56:57]
	s_waitcnt lgkmcnt(0)
	s_sub_u32 s56, s56, s52
	s_subb_u32 s57, s57, s53
	v_cmp_lt_u64_e32 vcc, s[56:57], v[142:143]
	s_cbranch_vccz .LBB0_228
	s_add_i32 s26, s26, 1
	s_mov_b64 s[58:59], 0
	s_nop 0
	s_branch .LBB0_228

.LBB0_1444:
	s_memrealtime s[22:23]
	s_waitcnt lgkmcnt(0)
	s_sub_u32 s22, s22, s8
	s_subb_u32 s23, s23, s9
	v_cmp_lt_u64_e32 vcc, s[22:23], v[2:3]
	s_cbranch_vccz .LBB0_1436
	s_add_i32 s11, s11, 1
	s_mov_b64 s[24:25], 0
	s_nop 0
	s_branch .LBB0_1436

.LBB0_1473:
	s_memrealtime s[58:59]
	s_waitcnt lgkmcnt(0)
	s_sub_u32 s58, s58, s56
	s_subb_u32 s59, s59, s57
	v_cmp_lt_u64_e32 vcc, s[58:59], v[142:143]
	s_cbranch_vccz .LBB0_1465
	s_add_i32 s26, s26, 1
	s_mov_b64 s[68:69], 0
	s_nop 0
	s_branch .LBB0_1465

.LBB0_1715:
	s_memrealtime s[14:15]
	s_waitcnt lgkmcnt(0)
	s_sub_u32 s14, s14, s8
	s_subb_u32 s15, s15, s9
	v_cmp_lt_u64_e32 vcc, s[14:15], v[2:3]
	s_cbranch_vccz .LBB0_1707
	s_add_i32 s20, s20, 1
	s_mov_b64 s[18:19], 0
	s_nop 0
	s_branch .LBB0_1707

.LBB0_1744:
	s_memrealtime s[68:69]
	s_waitcnt lgkmcnt(0)
	s_sub_u32 s68, s68, s58
	s_subb_u32 s69, s69, s59
	v_cmp_lt_u64_e32 vcc, s[68:69], v[142:143]
	s_cbranch_vccz .LBB0_1736
	s_add_i32 s20, s20, 1
	s_mov_b64 s[70:71], 0
	s_nop 0
	s_branch .LBB0_1736

.LBB0_2105:
	s_memrealtime s[20:21]
	s_waitcnt lgkmcnt(0)
	s_sub_u32 s20, s20, s8
	s_subb_u32 s21, s21, s9
	v_cmp_lt_u64_e32 vcc, s[20:21], v[2:3]
	s_cbranch_vccz .LBB0_2097
	s_add_i32 s15, s15, 1
	s_mov_b64 s[22:23], 0
	s_nop 0
	s_branch .LBB0_2097

.LBB0_2136:
	s_memrealtime s[48:49]
	s_waitcnt lgkmcnt(0)
	s_sub_u32 s48, s48, s46
	s_subb_u32 s49, s49, s47
	v_cmp_lt_u64_e32 vcc, s[48:49], v[110:111]
	s_cbranch_vccz .LBB0_2128
	s_add_i32 s22, s22, 1
	s_mov_b64 s[50:51], 0
	s_nop 0
	s_branch .LBB0_2128

.LBB0_3232:
	s_memrealtime s[66:67]
	s_waitcnt lgkmcnt(0)
	s_sub_u32 s66, s66, s58
	s_subb_u32 s67, s67, s59
	v_cmp_lt_u64_e32 vcc, s[66:67], v[110:111]
	s_cbranch_vccz .LBB0_3224
	s_add_i32 s24, s24, 1
	s_mov_b64 s[68:69], 0
	s_nop 0
	s_branch .LBB0_3224

.LBB0_3380:
	s_memrealtime s[66:67]
	s_waitcnt lgkmcnt(0)
	s_sub_u32 s66, s66, s58
	s_subb_u32 s67, s67, s59
	v_cmp_lt_u64_e32 vcc, s[66:67], v[142:143]
	s_cbranch_vccz .LBB0_3372
	s_add_i32 s20, s20, 1
	s_mov_b64 s[68:69], 0
	s_nop 0
	s_branch .LBB0_3372
